# v006 + P6 combine: late norm-weight loads hoisted to the top of the item (one dependent round trip less per item)
# speedup vs baseline: 1.0107x; 1.0032x over previous
; #define GAS __attribute__((address_space(1)))
; __device__ __forceinline__ unsigned pkbf(float lo, float hi) { unsigned r; asm volatile("v_cvt_pk_bf16_f32 %0, %1, %2" : "=v"(r) : "v"(lo), "v"(hi)); return r; }
; __device__ __forceinline__ float siluf_(float v) { return v * __builtin_amdgcn_rcpf(1.0f + __expf(-v)); }
; __device__ __forceinline__ void unpack8(const v4u w, float (&f)[8]) { f[0] = bflo(w.x); f[1] = bfhi(w.x); f[2] = bflo(w.y); f[3] = bfhi(w.y); f[4] = bflo(w.z); f[5] = bfhi(w.z); f[6] = bflo(w.w); f[7] = bfhi(w.w); }
; __device__ __forceinline__ void phase_ssm_combine(const Ctx& X, const bf16* yf, const bf16* yb, bf16* z, const float* normw) {
;     for (int it = X.gw; it < MTOK * SSM_G; it += X.NGW) {
;         const int tok = it >> 3, g = it & 7, e0 = g * 1024 + X.lane * 16;
;         float y[16];
; #pragma unroll
;         for (int hh = 0; hh < 2; ++hh) { float a[8], bq[8], zz[8];
;             unpack8(*(const GAS v4u*)(yf + (size_t)tok * SSM_DI + e0 + hh * 8), a); unpack8(*(const GAS v4u*)(yb + (size_t)tok * SSM_DI + e0 + hh * 8), bq);
;             unpack8(*(const GAS v4u*)(z + (size_t)tok * SSM_DI + e0 + hh * 8), zz);
; #pragma unroll
;             for (int j = 0; j < 8; ++j) y[hh * 8 + j] = (a[j] + bq[j]) * siluf_(zz[j]); }
;         float ss = 0.f;
; #pragma unroll
;         for (int j = 0; j < 16; ++j) ss += y[j] * y[j];
;         const float r = 1.0f / sqrtf(wave_sum(ss) * (1.f / 1024.f) + RMS_EPS);
; #pragma unroll
;         for (int hh = 0; hh < 2; ++hh) { float o[8];
; #pragma unroll
;             for (int j = 0; j < 8; ++j) o[j] = y[hh * 8 + j] * r * normw[e0 + hh * 8 + j];
;             v4u w; w.x = pkbf(o[0], o[1]); w.y = pkbf(o[2], o[3]); w.z = pkbf(o[4], o[5]); w.w = pkbf(o[6], o[7]);
;             *(GAS v4u*)(z + (size_t)tok * SSM_DI + e0 + hh * 8) = w; }
.LBB0_854:
	s_ashr_i32 s0, s6, 3
	s_and_b32 s1, s12, 0x1c00
	v_or_b32_e32 v0, s1, v10
	s_ashr_i32 s1, s0, 31
	s_lshl_b64 s[0:1], s[0:1], 14
	s_add_u32 s2, s92, s0
	v_lshlrev_b32_e32 v13, 1, v0
	v_lshlrev_b32_e32 v42, 2, v0
	s_addc_u32 s3, s93, s1
	global_load_dwordx4 v[0:3], v42, s[16:17] offset:16
	global_load_dwordx4 v[14:17], v42, s[16:17]
	global_load_dwordx4 v[68:71], v42, s[16:17] offset:32
	global_load_dwordx4 v[72:75], v42, s[16:17] offset:48
	global_load_dwordx4 v[18:21], v13, s[2:3]
	global_load_dwordx4 v[22:25], v13, s[2:3] offset:16
	s_add_u32 s2, s8, s0
	s_addc_u32 s3, s9, s1
	global_load_dwordx4 v[26:29], v13, s[2:3]
	global_load_dwordx4 v[30:33], v13, s[2:3] offset:16
	s_add_u32 s0, s10, s0
	s_addc_u32 s1, s11, s1
	global_load_dwordx4 v[34:37], v13, s[0:1]
	global_load_dwordx4 v[38:41], v13, s[0:1] offset:16
	s_add_i32 s6, s6, s7
	s_add_i32 s12, s12, s13
	s_cmp_lt_i32 s6, 0x20000
	s_waitcnt vmcnt(0)
	v_lshlrev_b32_e32 v43, 16, v18
	v_lshlrev_b32_e32 v50, 16, v25
	v_and_b32_e32 v25, 0xffff0000, v25
	v_and_b32_e32 v18, 0xffff0000, v18
	v_lshlrev_b32_e32 v58, 16, v33
	v_and_b32_e32 v33, 0xffff0000, v33
	v_lshlrev_b32_e32 v44, 16, v19
	v_lshlrev_b32_e32 v51, 16, v26
	v_and_b32_e32 v26, 0xffff0000, v26
	v_lshlrev_b32_e32 v52, 16, v27
	v_add_f32_e32 v25, v33, v25
	v_lshlrev_b32_e32 v33, 16, v34
	v_and_b32_e32 v34, 0xffff0000, v34
	v_add_f32_e32 v18, v26, v18
	v_add_f32_e32 v26, v52, v44
	v_mul_f32_e32 v52, 0xbfb8aa3b, v34
	v_and_b32_e32 v19, 0xffff0000, v19
	v_lshlrev_b32_e32 v45, 16, v20
	v_and_b32_e32 v27, 0xffff0000, v27
	v_lshlrev_b32_e32 v53, 16, v28
	v_add_f32_e32 v43, v51, v43
	v_lshlrev_b32_e32 v44, 16, v35
	v_mul_f32_e32 v51, 0xbfb8aa3b, v33
	v_exp_f32_e32 v52, v52
	v_and_b32_e32 v20, 0xffff0000, v20
	v_lshlrev_b32_e32 v46, 16, v21
	v_and_b32_e32 v28, 0xffff0000, v28
	v_lshlrev_b32_e32 v54, 16, v29
	v_add_f32_e32 v19, v27, v19
	v_add_f32_e32 v27, v53, v45
	v_and_b32_e32 v35, 0xffff0000, v35
	v_mul_f32_e32 v53, 0xbfb8aa3b, v44
	v_exp_f32_e32 v51, v51
	v_and_b32_e32 v21, 0xffff0000, v21
	v_lshlrev_b32_e32 v47, 16, v22
	v_and_b32_e32 v29, 0xffff0000, v29
	v_lshlrev_b32_e32 v55, 16, v30
	v_add_f32_e32 v20, v28, v20
	v_add_f32_e32 v28, v54, v46
	v_lshlrev_b32_e32 v45, 16, v36
	v_mul_f32_e32 v54, 0xbfb8aa3b, v35
	v_exp_f32_e32 v53, v53
	v_and_b32_e32 v22, 0xffff0000, v22
	v_lshlrev_b32_e32 v48, 16, v23
	v_and_b32_e32 v30, 0xffff0000, v30
	v_lshlrev_b32_e32 v56, 16, v31
	v_add_f32_e32 v21, v29, v21
	v_add_f32_e32 v29, v55, v47
	v_and_b32_e32 v36, 0xffff0000, v36
	v_mul_f32_e32 v55, 0xbfb8aa3b, v45
	v_exp_f32_e32 v54, v54
	v_and_b32_e32 v23, 0xffff0000, v23
	v_lshlrev_b32_e32 v49, 16, v24
	v_and_b32_e32 v31, 0xffff0000, v31
	v_lshlrev_b32_e32 v57, 16, v32
	v_add_f32_e32 v22, v30, v22
	v_add_f32_e32 v30, v56, v48
	v_lshlrev_b32_e32 v46, 16, v37
	v_mul_f32_e32 v56, 0xbfb8aa3b, v36
	v_exp_f32_e32 v55, v55
	v_add_f32_e32 v52, 1.0, v52
	v_and_b32_e32 v24, 0xffff0000, v24
	v_and_b32_e32 v32, 0xffff0000, v32
	v_add_f32_e32 v23, v31, v23
	v_add_f32_e32 v31, v57, v49
	v_and_b32_e32 v37, 0xffff0000, v37
	v_mul_f32_e32 v57, 0xbfb8aa3b, v46
	v_exp_f32_e32 v56, v56
	v_add_f32_e32 v51, 1.0, v51
	v_rcp_f32_e32 v52, v52
	v_add_f32_e32 v24, v32, v24
	v_add_f32_e32 v32, v58, v50
	v_lshlrev_b32_e32 v47, 16, v38
	v_mul_f32_e32 v58, 0xbfb8aa3b, v37
	v_exp_f32_e32 v57, v57
	v_add_f32_e32 v53, 1.0, v53
	v_rcp_f32_e32 v51, v51
	v_and_b32_e32 v38, 0xffff0000, v38
	v_mul_f32_e32 v59, 0xbfb8aa3b, v47
	v_exp_f32_e32 v58, v58
	v_add_f32_e32 v54, 1.0, v54
	v_rcp_f32_e32 v53, v53
	v_lshlrev_b32_e32 v48, 16, v39
	v_mul_f32_e32 v60, 0xbfb8aa3b, v38
	v_exp_f32_e32 v59, v59
	v_add_f32_e32 v55, 1.0, v55
	v_rcp_f32_e32 v54, v54
	v_and_b32_e32 v39, 0xffff0000, v39
	v_mul_f32_e32 v61, 0xbfb8aa3b, v48
	v_exp_f32_e32 v60, v60
	v_add_f32_e32 v56, 1.0, v56
	v_rcp_f32_e32 v55, v55
	v_mul_f32_e32 v34, v52, v34
	v_lshlrev_b32_e32 v49, 16, v40
	v_mul_f32_e32 v62, 0xbfb8aa3b, v39
	v_exp_f32_e32 v61, v61
	v_add_f32_e32 v57, 1.0, v57
	v_rcp_f32_e32 v56, v56
	v_mul_f32_e32 v33, v51, v33
	v_mul_f32_e32 v18, v18, v34
	v_and_b32_e32 v40, 0xffff0000, v40
	v_mul_f32_e32 v63, 0xbfb8aa3b, v49
	v_exp_f32_e32 v62, v62
	v_add_f32_e32 v58, 1.0, v58
	v_rcp_f32_e32 v57, v57
	v_mul_f32_e32 v44, v53, v44
	v_mul_f32_e32 v33, v43, v33
	v_mul_f32_e32 v34, v18, v18
	v_lshlrev_b32_e32 v50, 16, v41
	v_mul_f32_e32 v64, 0xbfb8aa3b, v40
	v_exp_f32_e32 v63, v63
	v_add_f32_e32 v59, 1.0, v59
	v_rcp_f32_e32 v58, v58
	v_mul_f32_e32 v35, v54, v35
	v_mul_f32_e32 v26, v26, v44
	v_fmac_f32_e32 v34, v33, v33
	v_and_b32_e32 v41, 0xffff0000, v41
	v_mul_f32_e32 v65, 0xbfb8aa3b, v50
	v_exp_f32_e32 v64, v64
	v_add_f32_e32 v60, 1.0, v60
	v_rcp_f32_e32 v59, v59
	v_mul_f32_e32 v45, v55, v45
	v_mul_f32_e32 v19, v19, v35
	v_fmac_f32_e32 v34, v26, v26
	v_mul_f32_e32 v66, 0xbfb8aa3b, v41
	v_exp_f32_e32 v65, v65
	v_add_f32_e32 v61, 1.0, v61
	v_rcp_f32_e32 v60, v60
	v_mul_f32_e32 v36, v56, v36
	v_mul_f32_e32 v27, v27, v45
	v_fmac_f32_e32 v34, v19, v19
	v_exp_f32_e32 v66, v66
	v_add_f32_e32 v62, 1.0, v62
	v_rcp_f32_e32 v61, v61
	v_mul_f32_e32 v46, v57, v46
	v_mul_f32_e32 v20, v20, v36
	v_fmac_f32_e32 v34, v27, v27
	v_add_f32_e32 v63, 1.0, v63
	v_rcp_f32_e32 v62, v62
	v_mul_f32_e32 v37, v58, v37
	v_mul_f32_e32 v28, v28, v46
	v_fmac_f32_e32 v34, v20, v20
	v_add_f32_e32 v64, 1.0, v64
	v_rcp_f32_e32 v63, v63
	v_mul_f32_e32 v47, v59, v47
	v_mul_f32_e32 v21, v21, v37
	v_fmac_f32_e32 v34, v28, v28
	v_add_f32_e32 v65, 1.0, v65
	v_rcp_f32_e32 v64, v64
	v_mul_f32_e32 v38, v60, v38
	v_mul_f32_e32 v29, v29, v47
	v_fmac_f32_e32 v34, v21, v21
	v_add_f32_e32 v66, 1.0, v66
	v_rcp_f32_e32 v65, v65
	v_mul_f32_e32 v48, v61, v48
	v_mul_f32_e32 v22, v22, v38
	v_fmac_f32_e32 v34, v29, v29
	v_rcp_f32_e32 v66, v66
	v_mul_f32_e32 v39, v62, v39
	v_mul_f32_e32 v30, v30, v48
	v_fmac_f32_e32 v34, v22, v22
	v_mul_f32_e32 v49, v63, v49
	v_mul_f32_e32 v23, v23, v39
	v_fmac_f32_e32 v34, v30, v30
	v_mul_f32_e32 v40, v64, v40
	v_mul_f32_e32 v31, v31, v49
	v_fmac_f32_e32 v34, v23, v23
	v_mul_f32_e32 v50, v65, v50
	v_mul_f32_e32 v24, v24, v40
	v_fmac_f32_e32 v34, v31, v31
	v_mul_f32_e32 v41, v66, v41
	v_mul_f32_e32 v32, v32, v50
	v_fmac_f32_e32 v34, v24, v24
	v_mul_f32_e32 v25, v25, v41
	v_fmac_f32_e32 v34, v32, v32
	v_fmac_f32_e32 v34, v25, v25
	ds_bpermute_b32 v35, v4, v34
	s_waitcnt lgkmcnt(0)
; #define GAS __attribute__((address_space(1)))
; __device__ __forceinline__ unsigned pkbf(float lo, float hi) { unsigned r; asm volatile("v_cvt_pk_bf16_f32 %0, %1, %2" : "=v"(r) : "v"(lo), "v"(hi)); return r; }
; __device__ __forceinline__ void phase_ssm_combine(const Ctx& X, const bf16* yf, const bf16* yb, bf16* z, const float* normw) {
;     ...
;         const float r = 1.0f / sqrtf(wave_sum(ss) * (1.f / 1024.f) + RMS_EPS);
; #pragma unroll
;         for (int hh = 0; hh < 2; ++hh) { float o[8];
; #pragma unroll
;             for (int j = 0; j < 8; ++j) o[j] = y[hh * 8 + j] * r * normw[e0 + hh * 8 + j];
;             v4u w; w.x = pkbf(o[0], o[1]); w.y = pkbf(o[2], o[3]); w.z = pkbf(o[4], o[5]); w.w = pkbf(o[6], o[7]);
;             *(GAS v4u*)(z + (size_t)tok * SSM_DI + e0 + hh * 8) = w; }
	v_add_f32_e32 v34, v34, v35
	ds_bpermute_b32 v35, v5, v34
	s_waitcnt lgkmcnt(0)
	v_add_f32_e32 v34, v34, v35
	ds_bpermute_b32 v35, v6, v34
	s_waitcnt lgkmcnt(0)
	v_add_f32_e32 v34, v34, v35
	ds_bpermute_b32 v35, v7, v34
	s_waitcnt lgkmcnt(0)
	v_add_f32_e32 v34, v34, v35
	ds_bpermute_b32 v35, v8, v34
	s_waitcnt lgkmcnt(0)
	v_add_f32_e32 v34, v34, v35
	ds_bpermute_b32 v35, v9, v34
	s_waitcnt lgkmcnt(0)
	v_add_f32_e32 v34, v34, v35
	v_fmamk_f32 v34, v34, 0x3a800000, v11
	v_mul_f32_e32 v35, 0x4f800000, v34
	v_cmp_gt_f32_e32 vcc, s14, v34
	s_nop 1
	v_cndmask_b32_e32 v34, v34, v35, vcc
	v_sqrt_f32_e32 v35, v34
	s_nop 0
	v_add_u32_e32 v36, -1, v35
	v_add_u32_e32 v37, 1, v35
	v_fma_f32 v38, -v36, v35, v34
	v_fma_f32 v39, -v37, v35, v34
	v_cmp_ge_f32_e64 s[2:3], 0, v38
	s_nop 1
	v_cndmask_b32_e64 v35, v35, v36, s[2:3]
	v_cmp_lt_f32_e64 s[2:3], 0, v39
	s_nop 1
	v_cndmask_b32_e64 v35, v35, v37, s[2:3]
	v_mul_f32_e32 v36, 0x37800000, v35
	v_cndmask_b32_e32 v35, v35, v36, vcc
	v_cmp_class_f32_e32 vcc, v34, v12
	s_nop 1
	v_cndmask_b32_e32 v34, v35, v34, vcc
	v_div_scale_f32 v35, s[2:3], v34, v34, 1.0
	v_rcp_f32_e32 v37, v35
	v_div_scale_f32 v36, vcc, 1.0, v34, 1.0
	v_fma_f32 v38, -v35, v37, 1.0
	v_fmac_f32_e32 v37, v38, v37
	v_mul_f32_e32 v38, v36, v37
	v_fma_f32 v39, -v35, v38, v36
	v_fmac_f32_e32 v38, v39, v37
	v_fma_f32 v35, -v35, v38, v36
	v_div_fmas_f32 v35, v35, v37, v38
	v_div_fixup_f32 v34, v35, v34, 1.0
	v_mul_f32_e32 v21, v21, v34
	v_mul_f32_e32 v33, v33, v34
	v_mul_f32_e32 v18, v18, v34
	v_mul_f32_e32 v26, v26, v34
	v_mul_f32_e32 v19, v19, v34
	v_mul_f32_e32 v27, v27, v34
	v_mul_f32_e32 v20, v20, v34
	v_mul_f32_e32 v28, v28, v34
	v_mul_f32_e32 v3, v3, v21
	v_mul_f32_e32 v14, v14, v33
	v_mul_f32_e32 v15, v15, v18
	v_mul_f32_e32 v16, v16, v26
	v_mul_f32_e32 v17, v17, v19
	v_mul_f32_e32 v18, v0, v27
	v_mul_f32_e32 v19, v1, v20
	v_mul_f32_e32 v20, v2, v28
	v_cvt_pk_bf16_f32 v0, v14, v15
	v_cvt_pk_bf16_f32 v1, v16, v17
	v_cvt_pk_bf16_f32 v2, v18, v19
	v_cvt_pk_bf16_f32 v3, v20, v3
	global_store_dwordx4 v13, v[0:3], s[0:1]
	v_mul_f32_e32 v18, v29, v34
	v_mul_f32_e32 v19, v22, v34
	v_mul_f32_e32 v20, v30, v34
	v_mul_f32_e32 v21, v23, v34
	v_mul_f32_e32 v22, v31, v34
	v_mul_f32_e32 v23, v24, v34
	v_mul_f32_e32 v24, v32, v34
	v_mul_f32_e32 v25, v25, v34
	v_mul_f32_e32 v0, v68, v18
	v_mul_f32_e32 v1, v69, v19
	v_mul_f32_e32 v2, v70, v20
	v_mul_f32_e32 v3, v71, v21
	v_mul_f32_e32 v14, v72, v22
	v_mul_f32_e32 v15, v73, v23
	v_mul_f32_e32 v16, v74, v24
	v_mul_f32_e32 v17, v75, v25
	v_cvt_pk_bf16_f32 v0, v0, v1
	v_cvt_pk_bf16_f32 v1, v2, v3
	v_cvt_pk_bf16_f32 v2, v14, v15
	v_cvt_pk_bf16_f32 v3, v16, v17
	global_store_dwordx4 v13, v[0:3], s[0:1] offset:16
	s_cbranch_scc1 .LBB0_854
